# QK^T K-tile LDS reads issued one pair ahead (second read buffer)
# baseline (speedup 1.0000x reference)
; __device__ __forceinline__ void finishSM(f32x16& p0, f32x16& p1, float alpha, float& l_reg, bf16x8& pa0, bf16x8& pa1, bf16x8& pa2, bf16x8& pa3) {
;     for (int r = 0; r < 16; ++r) p1[r] = __builtin_amdgcn_exp2f(p1[r]);
;     float ps = 0; for (int r = 0; r < 16; ++r) ps += p0[r]; for (int r = 0; r < 16; ++r) ps += p1[r];
; template <int KB>
; __device__ __forceinline__ void qkt(f32x16& p0, f32x16& p1, const char* K_lds, int r32, int hi, const bf16x8* qr) {
;     p0 = f32x16{}; p1 = f32x16{};
;     const char* kb[4];
; #pragma unroll
;     for (int dd = 0; dd < 4; ++dd) kb[dd] = K_lds + KB * SHM_K + KSWZ(r32, (dd * 16 + hi * 8) * 2);
; #pragma unroll
;     for (int d0 = 0; d0 < 8; ++d0) { const char* a = kb[d0 & 3] + (d0 >> 2) * 128;
;         bf16x8 b0 = *reinterpret_cast<const bf16x8*>(a);
;         bf16x8 b1 = *reinterpret_cast<const bf16x8*>(a + 32 * 256);
;         p0 = __builtin_amdgcn_mfma_f32_32x32x16_bf16(b0, qr[d0], p0, 0, 0, 0);
;         p1 = __builtin_amdgcn_mfma_f32_32x32x16_bf16(b1, qr[d0], p1, 0, 0, 0); }
; }
.LBB0_320:
	v_xor_b32_e32 v250, 0x80, v201
	v_xor_b32_e32 v251, 0x80, v230
	v_xor_b32_e32 v252, 0x80, v229
	v_xor_b32_e32 v253, 0x80, v207
	ds_read_b128 v[64:67], v201 offset:49152
	ds_read_b128 v[68:71], v201 offset:57344
	ds_read_b128 v[96:99], v230 offset:49152
	ds_read_b128 v[100:103], v230 offset:57344
	v_exp_f32_e32 v104, v126
	v_exp_f32_e32 v105, v127
	s_waitcnt lgkmcnt(3)
	v_mfma_f32_32x32x16_bf16 v[80:95], v[64:67], v[156:159], 0
	v_exp_f32_e32 v106, v122
	v_exp_f32_e32 v107, v123
	v_exp_f32_e32 v108, v118
	v_exp_f32_e32 v109, v119
	v_exp_f32_e32 v110, v116
	v_exp_f32_e32 v111, v117
	v_exp_f32_e32 v112, v112
	s_waitcnt lgkmcnt(2)
	v_mfma_f32_32x32x16_bf16 v[64:79], v[68:71], v[156:159], 0
	ds_read_b128 v[178:181], v229 offset:49152
	ds_read_b128 v[182:185], v229 offset:57344
	v_exp_f32_e32 v113, v113
	v_exp_f32_e32 v116, v124
	v_exp_f32_e32 v117, v125
	v_exp_f32_e32 v118, v120
	v_exp_f32_e32 v119, v121
	v_exp_f32_e32 v114, v114
	v_exp_f32_e32 v115, v115
	s_waitcnt lgkmcnt(3)
	v_mfma_f32_32x32x16_bf16 v[80:95], v[96:99], v[152:155], v[80:95]
	s_waitcnt lgkmcnt(2)
	v_mfma_f32_32x32x16_bf16 v[64:79], v[100:103], v[152:155], v[64:79]
	ds_read_b128 v[96:99], v207 offset:49152
	ds_read_b128 v[100:103], v207 offset:57344
	s_waitcnt lgkmcnt(3)
	v_mfma_f32_32x32x16_bf16 v[80:95], v[178:181], v[148:151], v[80:95]
	s_waitcnt lgkmcnt(2)
	v_mfma_f32_32x32x16_bf16 v[64:79], v[182:185], v[148:151], v[64:79]
	ds_read_b128 v[178:181], v250 offset:49152
	ds_read_b128 v[182:185], v250 offset:57344
	s_waitcnt lgkmcnt(3)
	v_mfma_f32_32x32x16_bf16 v[80:95], v[96:99], v[144:147], v[80:95]
	s_waitcnt lgkmcnt(2)
	v_mfma_f32_32x32x16_bf16 v[64:79], v[100:103], v[144:147], v[64:79]
	ds_read_b128 v[96:99], v251 offset:49152
	ds_read_b128 v[100:103], v251 offset:57344
	s_waitcnt lgkmcnt(3)
	v_mfma_f32_32x32x16_bf16 v[80:95], v[178:181], v[140:143], v[80:95]
	s_waitcnt lgkmcnt(2)
	v_mfma_f32_32x32x16_bf16 v[64:79], v[182:185], v[140:143], v[64:79]
	ds_read_b128 v[178:181], v252 offset:49152
	ds_read_b128 v[182:185], v252 offset:57344
	s_waitcnt lgkmcnt(3)
	v_mfma_f32_32x32x16_bf16 v[80:95], v[96:99], v[136:139], v[80:95]
	s_waitcnt lgkmcnt(2)
	v_mfma_f32_32x32x16_bf16 v[64:79], v[100:103], v[136:139], v[64:79]
	ds_read_b128 v[96:99], v253 offset:49152
	ds_read_b128 v[100:103], v253 offset:57344
	ds_read_b64_tr_b16 v[238:239], v225 offset:0
	ds_read_b64_tr_b16 v[240:241], v225 offset:0x800
	ds_read_b64_tr_b16 v[242:243], v225 offset:0x1000
	ds_read_b64_tr_b16 v[244:245], v225 offset:0x1800
	ds_read_b64_tr_b16 v[246:247], v225 offset:0x2000
	ds_read_b64_tr_b16 v[248:249], v225 offset:0x2800
	ds_read_b64_tr_b16 v[250:251], v225 offset:0x3000
	ds_read_b64_tr_b16 v[252:253], v225 offset:0x3800
	s_waitcnt lgkmcnt(11)
	v_mfma_f32_32x32x16_bf16 v[80:95], v[178:181], v[132:135], v[80:95]
	s_waitcnt lgkmcnt(10)
	v_mfma_f32_32x32x16_bf16 v[64:79], v[182:185], v[132:135], v[64:79]
	s_waitcnt lgkmcnt(9)
	v_mfma_f32_32x32x16_bf16 v[80:95], v[96:99], v[128:131], v[80:95]
	v_add_f32_e32 v96, 0, v169
	v_add_f32_e32 v96, v170, v96
	v_add_f32_e32 v96, v171, v96
	v_add_f32_e32 v96, v173, v96
	v_add_f32_e32 v96, v174, v96
	v_add_f32_e32 v96, v177, v96
	v_add_f32_e32 v96, v172, v96
	v_add_f32_e32 v96, v175, v96
	v_add_f32_e32 v96, v161, v96
	v_add_f32_e32 v96, v163, v96
	v_add_f32_e32 v96, v164, v96
	v_add_f32_e32 v96, v167, v96
	v_add_f32_e32 v96, v162, v96
	v_add_f32_e32 v96, v165, v96
	v_add_f32_e32 v96, v166, v96
	v_add_f32_e32 v96, v168, v96
	v_add_f32_e32 v96, v104, v96
	v_add_f32_e32 v96, v105, v96
	v_add_f32_e32 v96, v106, v96
	v_add_f32_e32 v96, v107, v96
	v_add_f32_e32 v96, v108, v96
	v_add_f32_e32 v96, v109, v96
	v_add_f32_e32 v96, v110, v96
	v_add_f32_e32 v96, v111, v96
	v_add_f32_e32 v96, v112, v96
	v_add_f32_e32 v96, v113, v96
	s_waitcnt lgkmcnt(8)
; __device__ __forceinline__ void finishSM(f32x16& p0, f32x16& p1, float alpha, float& l_reg, bf16x8& pa0, bf16x8& pa1, bf16x8& pa2, bf16x8& pa3) {
;     for (int r = 0; r < 16; ++r) p1[r] = __builtin_amdgcn_exp2f(p1[r]);
;     float ps = 0; for (int r = 0; r < 16; ++r) ps += p0[r]; for (int r = 0; r < 16; ++r) ps += p1[r];
;     { auto rr = __builtin_amdgcn_permlane32_swap(__float_as_uint(ps), __float_as_uint(ps), false, false);
;       ps = __uint_as_float(rr[0]) + __uint_as_float(rr[1]); }
;     l_reg = l_reg * alpha + ps;
;     ...
;     PK4(p0, 0, pa0); PK4(p0, 8, pa1); PK4(p1, 0, pa2); PK4(p1, 8, pa3);
;     ...
; }
; template <int KB>
; __device__ __forceinline__ void qkt(f32x16& p0, f32x16& p1, const char* K_lds, int r32, int hi, const bf16x8* qr) {
;     p0 = f32x16{}; p1 = f32x16{};
;     const char* kb[4];
; #pragma unroll
;     for (int dd = 0; dd < 4; ++dd) kb[dd] = K_lds + KB * SHM_K + KSWZ(r32, (dd * 16 + hi * 8) * 2);
; #pragma unroll
;     for (int d0 = 0; d0 < 8; ++d0) { const char* a = kb[d0 & 3] + (d0 >> 2) * 128;
;         bf16x8 b0 = *reinterpret_cast<const bf16x8*>(a);
;         bf16x8 b1 = *reinterpret_cast<const bf16x8*>(a + 32 * 256);
;         p0 = __builtin_amdgcn_mfma_f32_32x32x16_bf16(b0, qr[d0], p0, 0, 0, 0);
;         p1 = __builtin_amdgcn_mfma_f32_32x32x16_bf16(b1, qr[d0], p1, 0, 0, 0); }
; }
; template <int VB>
; __device__ __forceinline__ void pv_tile(f32x16* o, int vb0, bf16x8 pa0, bf16x8 pa1, bf16x8 pa2, bf16x8 pa3) {
;     ...
;     PV_D0(0); PV_D0(1); PV_D0(2); PV_D0(3);
;     ...
; }
	v_mfma_f32_32x32x16_bf16 v[64:79], v[100:103], v[128:131], v[64:79]
	v_add_f32_e32 v96, v116, v96
	v_add_f32_e32 v96, v117, v96
	v_add_f32_e32 v96, v118, v96
	v_add_f32_e32 v96, v119, v96
	v_add_f32_e32 v96, v114, v96
	v_add_f32_e32 v194, v115, v96
	v_mov_b32_e32 v234, v194
	v_cvt_pk_bf16_f32 v96, v169, v170
	v_cvt_pk_bf16_f32 v97, v171, v173
	v_cvt_pk_bf16_f32 v98, v174, v177
	v_cvt_pk_bf16_f32 v99, v172, v175
	v_permlane32_swap_b32_e32 v194, v234
	v_permlane32_swap_b32_e32 v96, v98
	v_permlane32_swap_b32_e32 v97, v99
	v_cvt_pk_bf16_f32 v100, v161, v163
	v_cvt_pk_bf16_f32 v101, v164, v167
	v_cvt_pk_bf16_f32 v102, v162, v165
	v_cvt_pk_bf16_f32 v103, v166, v168
	v_cvt_pk_bf16_f32 v104, v104, v105
	v_cvt_pk_bf16_f32 v105, v106, v107
	v_cvt_pk_bf16_f32 v106, v108, v109
	v_cvt_pk_bf16_f32 v107, v110, v111
	v_cvt_pk_bf16_f32 v108, v112, v113
	v_cvt_pk_bf16_f32 v109, v116, v117
	v_cvt_pk_bf16_f32 v110, v118, v119
	v_cvt_pk_bf16_f32 v111, v114, v115
	v_permlane32_swap_b32_e32 v100, v102
	v_permlane32_swap_b32_e32 v101, v103
	v_permlane32_swap_b32_e32 v104, v106
	v_permlane32_swap_b32_e32 v105, v107
	v_permlane32_swap_b32_e32 v108, v110
	v_permlane32_swap_b32_e32 v109, v111
	v_add_u32_e32 v212, s50, v202
	v_ashrrev_i32_e32 v213, 31, v212
	v_add_u32_e32 v116, 32, v212
	v_lshlrev_b64 v[112:113], 8, v[212:213]
	v_ashrrev_i32_e32 v117, 31, v116
	v_lshl_add_u64 v[114:115], v[208:209], 0, v[112:113]
	v_lshlrev_b64 v[116:117], 8, v[116:117]
	v_lshl_add_u64 v[112:113], v[210:211], 0, v[112:113]
	v_lshl_add_u64 v[118:119], v[208:209], 0, v[116:117]
	global_load_dwordx4 v[160:163], v[114:115], off
	global_load_dwordx4 v[164:167], v[118:119], off
	v_lshl_add_u64 v[114:115], v[210:211], 0, v[116:117]
	global_load_dwordx4 v[168:171], v[112:113], off
	global_load_dwordx4 v[172:175], v[114:115], off
	s_waitcnt lgkmcnt(0)
	s_nop 0
	v_mfma_f32_32x32x16_bf16 v[0:15], v[96:99], v[238:241], v[0:15]
	ds_read_b64_tr_b16 v[112:113], v225 offset:0x200
	ds_read_b64_tr_b16 v[114:115], v225 offset:0xa00
	v_mfma_f32_32x32x16_bf16 v[0:15], v[100:103], v[242:245], v[0:15]
	ds_read_b64_tr_b16 v[116:117], v225 offset:0x1200
	ds_read_b64_tr_b16 v[118:119], v225 offset:0x1a00
	v_mfma_f32_32x32x16_bf16 v[0:15], v[104:107], v[246:249], v[0:15]
	ds_read_b64_tr_b16 v[120:121], v225 offset:0x2200
	ds_read_b64_tr_b16 v[122:123], v225 offset:0x2a00
	v_mfma_f32_32x32x16_bf16 v[0:15], v[108:111], v[250:253], v[0:15]
	ds_read_b64_tr_b16 v[124:125], v225 offset:0x3200
	ds_read_b64_tr_b16 v[126:127], v225 offset:0x3a00
	s_waitcnt lgkmcnt(0)
	v_mfma_f32_32x32x16_bf16 v[48:63], v[96:99], v[112:115], v[48:63]
	ds_read_b64_tr_b16 v[112:113], v225 offset:0x400
	ds_read_b64_tr_b16 v[114:115], v225 offset:0xc00
	v_mfma_f32_32x32x16_bf16 v[48:63], v[100:103], v[116:119], v[48:63]
	ds_read_b64_tr_b16 v[116:117], v225 offset:0x1400
	ds_read_b64_tr_b16 v[118:119], v225 offset:0x1c00
	v_mfma_f32_32x32x16_bf16 v[48:63], v[104:107], v[120:123], v[48:63]
	ds_read_b64_tr_b16 v[120:121], v225 offset:0x2400
	ds_read_b64_tr_b16 v[122:123], v225 offset:0x2c00
	v_mfma_f32_32x32x16_bf16 v[48:63], v[108:111], v[124:127], v[48:63]
	ds_read_b64_tr_b16 v[124:125], v225 offset:0x3400
	ds_read_b64_tr_b16 v[126:127], v225 offset:0x3c00
	s_waitcnt lgkmcnt(0)
	v_mfma_f32_32x32x16_bf16 v[32:47], v[96:99], v[112:115], v[32:47]
	ds_read_b64_tr_b16 v[112:113], v225 offset:0x600
	ds_read_b64_tr_b16 v[114:115], v225 offset:0xe00
	v_mfma_f32_32x32x16_bf16 v[32:47], v[100:103], v[116:119], v[32:47]
	ds_read_b64_tr_b16 v[116:117], v225 offset:0x1600
	ds_read_b64_tr_b16 v[118:119], v225 offset:0x1e00
	v_mfma_f32_32x32x16_bf16 v[32:47], v[104:107], v[120:123], v[32:47]
	ds_read_b64_tr_b16 v[120:121], v225 offset:0x2600
	ds_read_b64_tr_b16 v[122:123], v225 offset:0x2e00
	v_mfma_f32_32x32x16_bf16 v[32:47], v[108:111], v[124:127], v[32:47]
	ds_read_b64_tr_b16 v[124:125], v225 offset:0x3600
	ds_read_b64_tr_b16 v[126:127], v225 offset:0x3e00
	s_waitcnt lgkmcnt(0)
	s_waitcnt vmcnt(0)
	ds_write_b128 v231, v[160:163] offset:16384
	ds_write_b128 v232, v[164:167] offset:16384
	ds_write_b128 v226, v[168:171] offset:32768
	ds_write_b128 v226, v[172:175] offset:40960
	s_sub_i32 s40, s50, 64
	s_cmp_gt_i32 s40, s49
	s_cbranch_scc0 .Lmy_nomask1
	v_mov_b32_e32 v64, v220
	v_mov_b32_e32 v65, v220
	v_mov_b32_e32 v66, v220
	v_mov_b32_e32 v67, v220
	v_mov_b32_e32 v68, v220
	v_mov_b32_e32 v69, v220
	v_mov_b32_e32 v70, v220
	v_mov_b32_e32 v71, v220
	v_mov_b32_e32 v72, v220
	v_mov_b32_e32 v73, v220
	v_mov_b32_e32 v74, v220
	v_mov_b32_e32 v75, v220
	v_mov_b32_e32 v76, v220
	v_mov_b32_e32 v77, v220
	v_mov_b32_e32 v78, v220
	v_mov_b32_e32 v79, v220
	v_mov_b32_e32 v80, v220
	v_mov_b32_e32 v81, v220
	v_mov_b32_e32 v82, v220
	v_mov_b32_e32 v83, v220
	v_mov_b32_e32 v84, v220
	v_mov_b32_e32 v85, v220
	v_mov_b32_e32 v86, v220
	v_mov_b32_e32 v87, v220
	v_mov_b32_e32 v88, v220
	v_mov_b32_e32 v89, v220
	v_mov_b32_e32 v90, v220
	v_mov_b32_e32 v91, v220
	v_mov_b32_e32 v92, v220
	v_mov_b32_e32 v93, v220
	v_mov_b32_e32 v94, v220
	v_mov_b32_e32 v95, v220

; __device__ __forceinline__ void partialSM(f32x16& p0, f32x16& p1, float& m_reg, float& mn, float& alpha) {
;     ...
;     if (__builtin_expect(__all((pmax - m_reg) * SCALE <= THR), 1)) { mn = m_reg; alpha = 1.f; }
;     else { mn = fmaxf(m_reg, pmax); alpha = __builtin_amdgcn_exp2f((m_reg - mn) * C2); m_reg = mn; }
;     const float mnL = -mn * C2;
;     for (int r = 0; r < 16; ++r) p0[r] = fmaf(p0[r], C2, mnL); for (int r = 0; r < 16; ++r) p1[r] = fmaf(p1[r], C2, mnL);
;     for (int r = 0; r < 16; ++r) p0[r] = __builtin_amdgcn_exp2f(p0[r]);
.LBB0_324:
	v_cndmask_b32_e64 v235, v77, v176, s[40:41]
	v_mul_f32_e32 v176, 0xbe0293ee, v235
	v_fmamk_f32 v77, v98, 0x3e0293ee, v176
	v_fmamk_f32 v78, v97, 0x3e0293ee, v176
	v_fmamk_f32 v79, v96, 0x3e0293ee, v176
	v_fmamk_f32 v96, v83, 0x3e0293ee, v176
	v_fmamk_f32 v97, v84, 0x3e0293ee, v176
	v_fmamk_f32 v98, v85, 0x3e0293ee, v176
	v_fmamk_f32 v99, v86, 0x3e0293ee, v176
	v_fmamk_f32 v100, v87, 0x3e0293ee, v176
	v_fmamk_f32 v101, v88, 0x3e0293ee, v176
	v_fmamk_f32 v102, v89, 0x3e0293ee, v176
	v_fmamk_f32 v103, v90, 0x3e0293ee, v176
	v_fmamk_f32 v104, v91, 0x3e0293ee, v176
	v_fmamk_f32 v105, v92, 0x3e0293ee, v176
	v_fmamk_f32 v106, v93, 0x3e0293ee, v176
	v_fmamk_f32 v107, v94, 0x3e0293ee, v176
	v_fmamk_f32 v108, v95, 0x3e0293ee, v176
	v_fmamk_f32 v83, v64, 0x3e0293ee, v176
	v_fmamk_f32 v84, v65, 0x3e0293ee, v176
	v_fmamk_f32 v93, v66, 0x3e0293ee, v176
	v_fmamk_f32 v94, v67, 0x3e0293ee, v176
	v_fmamk_f32 v95, v68, 0x3e0293ee, v176
	v_fmamk_f32 v85, v69, 0x3e0293ee, v176
	v_fmamk_f32 v86, v70, 0x3e0293ee, v176
	v_fmamk_f32 v87, v71, 0x3e0293ee, v176
	v_fmamk_f32 v88, v72, 0x3e0293ee, v176
	v_fmamk_f32 v89, v73, 0x3e0293ee, v176
	v_fmamk_f32 v90, v74, 0x3e0293ee, v176
	v_fmamk_f32 v91, v75, 0x3e0293ee, v176
	v_fmamk_f32 v92, v76, 0x3e0293ee, v176
	v_exp_f32_e32 v64, v77
	v_exp_f32_e32 v65, v78
	v_exp_f32_e32 v66, v79
	v_exp_f32_e32 v67, v96
	v_exp_f32_e32 v68, v97
	v_exp_f32_e32 v69, v98
	v_exp_f32_e32 v70, v99
	v_exp_f32_e32 v71, v100
	v_exp_f32_e32 v72, v101
	v_exp_f32_e32 v73, v102
	v_exp_f32_e32 v74, v103
	v_exp_f32_e32 v75, v104
	v_exp_f32_e32 v76, v105
	v_exp_f32_e32 v77, v106
	v_exp_f32_e32 v78, v107
	v_exp_f32_e32 v79, v108
	v_fmamk_f32 v177, v82, 0x3e0293ee, v176
	v_fmamk_f32 v178, v81, 0x3e0293ee, v176
	v_fmac_f32_e32 v176, 0x3e0293ee, v80
	s_waitcnt lgkmcnt(0)
	s_barrier
; __device__ __forceinline__ void finishSM(f32x16& p0, f32x16& p1, float alpha, float& l_reg, bf16x8& pa0, bf16x8& pa1, bf16x8& pa2, bf16x8& pa3) {
;     for (int r = 0; r < 16; ++r) p1[r] = __builtin_amdgcn_exp2f(p1[r]);
;     float ps = 0; for (int r = 0; r < 16; ++r) ps += p0[r]; for (int r = 0; r < 16; ++r) ps += p1[r];
;     { auto rr = __builtin_amdgcn_permlane32_swap(__float_as_uint(ps), __float_as_uint(ps), false, false);
;       ps = __uint_as_float(rr[0]) + __uint_as_float(rr[1]); }
;     l_reg = l_reg * alpha + ps;
;     ...
;     PK4(p0, 0, pa0); PK4(p0, 8, pa1); PK4(p1, 0, pa2); PK4(p1, 8, pa3);
; template <int KB>
; __device__ __forceinline__ void qkt(f32x16& p0, f32x16& p1, const char* K_lds, int r32, int hi, const bf16x8* qr) {
;     p0 = f32x16{}; p1 = f32x16{};
;     const char* kb[4];
; #pragma unroll
;     for (int dd = 0; dd < 4; ++dd) kb[dd] = K_lds + KB * SHM_K + KSWZ(r32, (dd * 16 + hi * 8) * 2);
; #pragma unroll
;     for (int d0 = 0; d0 < 8; ++d0) { const char* a = kb[d0 & 3] + (d0 >> 2) * 128;
;         bf16x8 b0 = *reinterpret_cast<const bf16x8*>(a);
;         bf16x8 b1 = *reinterpret_cast<const bf16x8*>(a + 32 * 256);
;         p0 = __builtin_amdgcn_mfma_f32_32x32x16_bf16(b0, qr[d0], p0, 0, 0, 0);
;         p1 = __builtin_amdgcn_mfma_f32_32x32x16_bf16(b1, qr[d0], p1, 0, 0, 0); }
; }
	v_xor_b32_e32 v250, 0x80, v201
	v_xor_b32_e32 v251, 0x80, v230
	v_xor_b32_e32 v252, 0x80, v229
	v_xor_b32_e32 v253, 0x80, v207
	ds_read_b128 v[96:99], v201 offset:32768
	ds_read_b128 v[100:103], v201 offset:40960
	ds_read_b128 v[180:183], v230 offset:32768
	ds_read_b128 v[184:187], v230 offset:40960
	v_exp_f32_e32 v81, v84
	v_exp_f32_e32 v84, v95
	s_waitcnt lgkmcnt(3)
	v_mfma_f32_32x32x16_bf16 v[112:127], v[96:99], v[156:159], 0
	v_exp_f32_e32 v95, v176
	v_add_f32_e32 v176, 0, v64
	v_add_f32_e32 v176, v65, v176
	v_add_f32_e32 v176, v66, v176
	v_add_f32_e32 v176, v67, v176
	v_add_f32_e32 v176, v68, v176
	v_add_f32_e32 v176, v69, v176
	s_waitcnt lgkmcnt(2)
	v_mfma_f32_32x32x16_bf16 v[96:111], v[100:103], v[156:159], 0
	ds_read_b128 v[160:163], v229 offset:32768
	ds_read_b128 v[164:167], v229 offset:40960
	v_add_f32_e32 v176, v70, v176
	v_add_f32_e32 v176, v71, v176
	v_add_f32_e32 v176, v72, v176
	v_add_f32_e32 v176, v73, v176
	v_add_f32_e32 v176, v74, v176
	v_add_f32_e32 v176, v75, v176
	v_exp_f32_e32 v80, v83
	s_waitcnt lgkmcnt(3)
	v_mfma_f32_32x32x16_bf16 v[112:127], v[180:183], v[152:155], v[112:127]
	v_add_f32_e32 v176, v76, v176
	v_add_f32_e32 v176, v77, v176
	v_exp_f32_e32 v82, v93
	v_add_f32_e32 v176, v78, v176
	v_exp_f32_e32 v83, v94
	v_add_f32_e32 v176, v79, v176
	v_add_f32_e32 v176, v80, v176
	s_waitcnt lgkmcnt(2)
	v_mfma_f32_32x32x16_bf16 v[96:111], v[184:187], v[152:155], v[96:111]
	ds_read_b128 v[180:183], v207 offset:32768
	ds_read_b128 v[184:187], v207 offset:40960
	v_exp_f32_e32 v85, v85
	v_add_f32_e32 v176, v81, v176
	v_exp_f32_e32 v86, v86
	v_add_f32_e32 v176, v82, v176
	v_exp_f32_e32 v87, v87
	v_add_f32_e32 v176, v83, v176
	s_waitcnt lgkmcnt(3)
	v_mfma_f32_32x32x16_bf16 v[112:127], v[160:163], v[148:151], v[112:127]
	v_exp_f32_e32 v88, v88
	v_add_f32_e32 v176, v84, v176
	v_exp_f32_e32 v89, v89
	v_add_f32_e32 v176, v85, v176
	v_exp_f32_e32 v90, v90
	v_add_f32_e32 v176, v86, v176
	v_exp_f32_e32 v91, v91
	s_waitcnt lgkmcnt(2)
	v_mfma_f32_32x32x16_bf16 v[96:111], v[164:167], v[148:151], v[96:111]
	ds_read_b128 v[160:163], v250 offset:32768
	ds_read_b128 v[164:167], v250 offset:40960
	v_add_f32_e32 v176, v87, v176
	v_exp_f32_e32 v92, v92
	v_add_f32_e32 v176, v88, v176
	v_exp_f32_e32 v93, v177
	v_add_f32_e32 v176, v89, v176
	v_exp_f32_e32 v94, v178
	s_waitcnt lgkmcnt(3)
	v_mfma_f32_32x32x16_bf16 v[112:127], v[180:183], v[144:147], v[112:127]
	v_add_f32_e32 v176, v90, v176
	v_add_f32_e32 v176, v91, v176
	v_add_f32_e32 v176, v92, v176
	v_add_f32_e32 v176, v93, v176
	v_add_f32_e32 v176, v94, v176
	v_add_f32_e32 v236, v95, v176
	v_mov_b32_e32 v237, v236
	s_waitcnt lgkmcnt(2)
	v_mfma_f32_32x32x16_bf16 v[96:111], v[184:187], v[144:147], v[96:111]
	ds_read_b128 v[180:183], v251 offset:32768
	ds_read_b128 v[184:187], v251 offset:40960
	v_cvt_pk_bf16_f32 v176, v64, v65
	v_cvt_pk_bf16_f32 v177, v66, v67
	v_cvt_pk_bf16_f32 v178, v68, v69
	v_cvt_pk_bf16_f32 v179, v70, v71
	v_cvt_pk_bf16_f32 v188, v88, v89
	v_cvt_pk_bf16_f32 v189, v90, v91
	s_waitcnt lgkmcnt(3)
	v_mfma_f32_32x32x16_bf16 v[112:127], v[160:163], v[140:143], v[112:127]
	v_cvt_pk_bf16_f32 v190, v92, v93
	v_cvt_pk_bf16_f32 v191, v94, v95
	v_permlane32_swap_b32_e32 v236, v237
	v_permlane32_swap_b32_e32 v176, v178
	v_permlane32_swap_b32_e32 v177, v179
	s_waitcnt lgkmcnt(2)
	v_mfma_f32_32x32x16_bf16 v[96:111], v[164:167], v[140:143], v[96:111]
	ds_read_b128 v[160:163], v252 offset:32768
	ds_read_b128 v[164:167], v252 offset:40960
	v_permlane32_swap_b32_e32 v188, v190
	v_permlane32_swap_b32_e32 v189, v191
	s_waitcnt lgkmcnt(3)
	v_mfma_f32_32x32x16_bf16 v[112:127], v[180:183], v[136:139], v[112:127]
	s_waitcnt lgkmcnt(2)
	v_mfma_f32_32x32x16_bf16 v[96:111], v[184:187], v[136:139], v[96:111]
	ds_read_b128 v[180:183], v253 offset:32768
	ds_read_b128 v[184:187], v253 offset:40960
	ds_read_b64_tr_b16 v[238:239], v225 offset:0x4000
	ds_read_b64_tr_b16 v[240:241], v225 offset:0x4800
	ds_read_b64_tr_b16 v[242:243], v225 offset:0x5000
	ds_read_b64_tr_b16 v[244:245], v225 offset:0x5800
	ds_read_b64_tr_b16 v[246:247], v225 offset:0x6000
	ds_read_b64_tr_b16 v[248:249], v225 offset:0x6800
	ds_read_b64_tr_b16 v[250:251], v225 offset:0x7000
	ds_read_b64_tr_b16 v[252:253], v225 offset:0x7800
	s_waitcnt lgkmcnt(11)
	v_mfma_f32_32x32x16_bf16 v[112:127], v[160:163], v[132:135], v[112:127]
	s_waitcnt lgkmcnt(10)
	v_mfma_f32_32x32x16_bf16 v[96:111], v[164:167], v[132:135], v[96:111]
	s_waitcnt lgkmcnt(9)
	v_mfma_f32_32x32x16_bf16 v[112:127], v[180:183], v[128:131], v[112:127]
	v_cvt_pk_bf16_f32 v180, v72, v73
	v_cvt_pk_bf16_f32 v181, v74, v75
	v_cvt_pk_bf16_f32 v182, v76, v77
	v_cvt_pk_bf16_f32 v183, v78, v79
	s_nop 0
	v_permlane32_swap_b32_e32 v180, v182
	v_permlane32_swap_b32_e32 v181, v183
	s_waitcnt lgkmcnt(8)
	v_mfma_f32_32x32x16_bf16 v[96:111], v[184:187], v[128:131], v[96:111]
	v_cvt_pk_bf16_f32 v184, v80, v81
	v_cvt_pk_bf16_f32 v185, v82, v83
	v_cvt_pk_bf16_f32 v186, v84, v85
	v_cvt_pk_bf16_f32 v187, v86, v87
	s_nop 0
	v_permlane32_swap_b32_e32 v184, v186
	v_permlane32_swap_b32_e32 v185, v187
	s_add_i32 s40, s80, 1
	s_cmp_lt_u32 s40, s79
	s_cselect_b64 s[42:43], -1, 0
	s_cmp_ge_u32 s40, s79
	s_cbranch_scc1 .LBB0_326
	v_add_u32_e32 v160, 64, v212
	v_add_u32_e32 v162, 0x60, v212
	v_ashrrev_i32_e32 v161, 31, v160
	v_ashrrev_i32_e32 v163, 31, v162
	v_lshlrev_b64 v[168:169], 8, v[160:161]
	v_lshlrev_b64 v[170:171], 8, v[162:163]
	v_lshl_add_u64 v[160:161], v[208:209], 0, v[168:169]
	v_lshl_add_u64 v[164:165], v[208:209], 0, v[170:171]
	v_lshl_add_u64 v[168:169], v[210:211], 0, v[168:169]
	v_lshl_add_u64 v[172:173], v[210:211], 0, v[170:171]
	global_load_dwordx4 v[160:163], v[160:161], off
	s_nop 0
	global_load_dwordx4 v[164:167], v[164:165], off
	s_nop 0
	global_load_dwordx4 v[168:171], v[168:169], off
	s_nop 0
	global_load_dwordx4 v[172:175], v[172:173], off
